# fin2_pad + static s_setprio 1 for waves 0-3 during the attention KV loop
# baseline (speedup 1.0000x reference)
.LBB0_397:
	s_and_b32 s45, s0, 15
	s_ashr_i32 s37, s36, 31
	s_mul_i32 s3, s36, 0x1800
	s_mul_hi_i32 s1, s36, 0x1800
	s_add_u32 s3, s78, s3
	v_readlane_b32 s2, v252, 50
	s_addc_u32 s1, s2, s1
	s_lshl_b32 s5, s45, 7
	s_add_u32 s30, s3, s5
	s_addc_u32 s31, s1, 0
	v_readlane_b32 s2, v250, 19
	v_readlane_b32 s3, v250, 20
	s_add_u32 s28, s2, s5
	v_mov_b32_e32 v6, v168
	s_addc_u32 s29, s3, 0
	s_lshl_b32 s0, s0, 7
	s_and_b32 s0, s0, 0x700
	v_ashrrev_i32_e32 v0, 6, v6
	v_and_b32_e32 v62, 63, v6
	v_and_b32_e32 v1, 0x3fffffc0, v6
	v_and_b32_e32 v200, 31, v6
	v_lshl_add_u32 v175, v1, 2, v192
	v_lshl_add_u32 v1, v0, 12, v192
	v_lshlrev_b32_e32 v7, 4, v62
	v_lshlrev_b32_e32 v174, 5, v0
	s_add_u32 s39, s73, s0
	v_bfe_u32 v201, v6, 5, 1
	v_add_u32_e32 v204, v1, v7
	v_or_b32_e32 v2, v174, v200
	v_mov_b64_e32 v[0:1], s[30:31]
	s_movk_i32 s0, 0x1800
	v_mad_i64_i32 v[0:1], s[0:1], v2, s0, v[0:1]
	v_lshlrev_b32_e32 v176, 4, v201
	v_mov_b32_e32 v177, v171
	v_lshl_add_u64 v[4:5], v[0:1], 0, v[176:177]
	global_load_dwordx4 v[0:3], v[4:5], off
	v_lshlrev_b32_e32 v12, 3, v6
	s_movk_i32 s1, 0xe0
	s_mov_b32 s0, 0x7ffffc
	s_addc_u32 s42, s63, 0
	s_cmp_lg_u32 0x100, -1
	s_mul_i32 s44, s38, 0x1800
	s_mul_hi_i32 s43, s38, 0x1800
	v_and_b32_e32 v8, 0x70, v6
	v_lshlrev_b32_e32 v72, 7, v200
	v_and_b32_e32 v73, 0x70, v12
	v_or_b32_e32 v64, 32, v176
	v_bitop3_b32 v64, v64, v72, v73 bitop3:0xde
	v_add_u32_e32 v209, 0x100, v64
	s_mov_b32 s5, s4
	s_mov_b32 s10, s4
	s_mov_b32 s11, s4
	s_mov_b32 s12, s4
	s_mov_b32 s13, s4
	s_mov_b32 s14, s4
	s_mov_b32 s15, s4
	s_mov_b32 s16, s4
	s_mov_b32 s17, s4
	s_mov_b32 s18, s4
	s_mov_b32 s19, s4
	v_mov_b32_e32 v61, v171
	v_cmp_gt_u32_e64 s[40:41], 32, v62
	s_mov_b32 s50, 4
	s_movk_i32 s51, 0xc0
	v_lshl_add_u32 v177, v200, 2, v175
	v_mov_b32_e32 v178, 0
	s_waitcnt vmcnt(0)
	ds_write_b128 v204, v[0:3] offset:51200
	global_load_dwordx4 v[0:3], v[4:5], off offset:32
	s_waitcnt vmcnt(0)
	ds_write_b128 v204, v[0:3] offset:52224
	global_load_dwordx4 v[0:3], v[4:5], off offset:64
	s_waitcnt vmcnt(0)
	ds_write_b128 v204, v[0:3] offset:53248
	global_load_dwordx4 v[0:3], v[4:5], off offset:96
	v_and_b32_e32 v5, 24, v12
	s_waitcnt vmcnt(0)
	ds_write_b128 v204, v[0:3] offset:54272
	v_ashrrev_i32_e32 v0, 4, v6
	v_lshlrev_b32_e32 v4, 5, v0
	v_lshrrev_b32_e32 v2, 5, v6
	v_bfe_u32 v3, v12, 5, 2
	v_and_or_b32 v4, v4, s1, v5
	v_and_or_b32 v2, v2, s0, v3
	v_lshlrev_b32_e32 v4, 1, v4
	v_lshl_or_b32 v13, v2, 9, v4
	v_add_u32_e32 v2, 32, v0
	v_lshrrev_b32_e32 v2, 1, v2
	v_and_or_b32 v2, v2, s0, v3
	s_movk_i32 s0, 0xc00
	v_and_b32_e32 v1, 0x78, v12
	v_mul_lo_u32 v0, v0, s0
	v_lshl_or_b32 v14, v2, 9, v4
	v_ashrrev_i32_e32 v2, 3, v6
	v_or_b32_e32 v0, v0, v1
	v_and_b32_e32 v3, 56, v12
	v_lshlrev_b32_e32 v170, 1, v0
	v_mul_lo_u32 v0, v2, s0
	v_or_b32_e32 v0, v0, v3
	s_cselect_b32 s0, 0x100, 0
	s_add_u32 s6, s39, s44
	v_lshlrev_b32_e32 v4, 7, v2
	v_lshlrev_b32_e32 v5, 1, v3
	v_lshlrev_b32_e32 v60, 1, v0
	v_lshlrev_b32_e32 v0, 3, v62
	v_and_b32_e32 v1, 0xc0, v7
	v_lshlrev_b32_e32 v2, 1, v6
	s_addc_u32 s7, s42, s43
	v_bitop3_b32 v15, v5, v4, v8 bitop3:0xde
	v_and_or_b32 v1, v0, 24, v1
	v_and_b32_e32 v2, 32, v2
	v_and_b32_e32 v0, 0x100, v0
	v_lshl_add_u64 v[4:5], s[6:7], 0, v[170:171]
	v_or3_b32 v63, v1, v2, v0
	s_add_u32 s8, s28, s44
	global_load_dwordx4 v[0:3], v170, s[6:7]
	v_add_co_u32_e32 v4, vcc, s33, v4
	s_addc_u32 s9, s29, s43
	s_nop 0
	v_addc_co_u32_e32 v5, vcc, 0, v5, vcc
	global_load_dwordx4 v[4:7], v[4:5], off
	v_add_u32_e32 v205, 0x100, v13
	global_load_dwordx4 v[8:11], v60, s[8:9]
	s_waitcnt vmcnt(0)
	v_add_u32_e32 v206, 0x100, v14
	v_add_u32_e32 v207, 0x100, v15
	s_mov_b32 s6, s4
	s_mov_b32 s7, s4
	s_mov_b32 s8, s4
	s_mov_b32 s9, s4
	s_add_i32 s1, s38, 64
	v_add_u32_e32 v203, s0, v63
	v_lshl_add_u64 v[180:181], s[28:29], 0, v[60:61]
	s_waitcnt vmcnt(2)
	ds_write_b128 v205, v[0:3]
	v_bitop3_b32 v0, v176, v72, v73 bitop3:0xde
	v_add_u32_e32 v208, 0x100, v0
	s_waitcnt vmcnt(1)
	ds_write_b128 v206, v[4:7]
	s_waitcnt vmcnt(0)
	ds_write_b128 v207, v[8:11] offset:32768
	s_waitcnt lgkmcnt(0)
	s_barrier
	ds_read_b128 v[56:59], v204 offset:52224
	ds_read_b128 v[52:55], v204 offset:53248
	ds_read_b128 v[48:51], v204 offset:54272
	ds_read_b128 v[16:19], v208 offset:36864
	ds_read_b128 v[20:23], v208 offset:32768
	ds_read_b128 v[24:27], v204 offset:51200
	s_waitcnt lgkmcnt(0)
	v_mfma_f32_32x32x16_bf16 v[32:47], v[20:23], v[24:27], 0
	ds_read_b128 v[64:67], v209 offset:36864
	ds_read_b128 v[68:71], v209 offset:32768
	v_mov_b64_e32 v[0:1], s[4:5]
	v_mov_b64_e32 v[2:3], s[6:7]
	v_mov_b64_e32 v[4:5], s[8:9]
	v_mov_b64_e32 v[6:7], s[10:11]
	v_mov_b64_e32 v[8:9], s[12:13]
	v_mov_b64_e32 v[10:11], s[14:15]
	v_mfma_f32_32x32x16_bf16 v[16:31], v[16:19], v[24:27], 0
	v_mov_b64_e32 v[12:13], s[16:17]
	v_mov_b64_e32 v[14:15], s[18:19]
	s_add_i32 s12, s44, 0x60000
	s_mul_hi_i32 s5, s1, 0x1800
	s_add_u32 s6, s39, s12
	s_addc_u32 s7, s42, s5
	s_add_u32 s8, s28, s12
	s_waitcnt lgkmcnt(0)
	v_mfma_f32_32x32x16_bf16 v[32:47], v[68:71], v[56:59], v[32:47]
	s_addc_u32 s9, s29, s5
	s_add_i32 s1, s38, 0x80
	s_add_i32 s47, s44, 0xc0000
	s_mul_hi_i32 s46, s1, 0x1800
	v_mfma_f32_32x32x16_bf16 v[16:31], v[64:67], v[56:59], v[16:31]
	v_or_b32_e32 v56, 64, v176
	v_bitop3_b32 v56, v56, v72, v73 bitop3:0xde
	v_add_u32_e32 v210, 0x100, v56
	ds_read_b128 v[56:59], v210 offset:36864
	ds_read_b128 v[64:67], v210 offset:32768
	s_waitcnt lgkmcnt(0)
	v_mfma_f32_32x32x16_bf16 v[32:47], v[64:67], v[52:55], v[32:47]
	v_mfma_f32_32x32x16_bf16 v[16:31], v[56:59], v[52:55], v[16:31]
	v_or_b32_e32 v52, 0x60, v176
	v_bitop3_b32 v52, v52, v72, v73 bitop3:0xde
	v_add_u32_e32 v211, 0x100, v52
	ds_read_b128 v[52:55], v211 offset:36864
	ds_read_b128 v[56:59], v211 offset:32768
	s_waitcnt lgkmcnt(0)
	v_mfma_f32_32x32x16_bf16 v[32:47], v[56:59], v[48:51], v[32:47]
	v_mfma_f32_32x32x16_bf16 v[16:31], v[52:55], v[48:51], v[16:31]
	s_nop 10
	v_max_f32_e32 v48, v33, v33
	v_max_f32_e32 v49, v32, v32
	v_max_f32_e32 v48, v49, v48
	v_max3_f32 v48, v48, v34, v35
	v_max3_f32 v48, v48, v36, v37
	v_max3_f32 v48, v48, v38, v39
	v_max3_f32 v48, v48, v40, v41
	v_max3_f32 v48, v48, v42, v43
	v_max3_f32 v48, v48, v44, v45
	v_max3_f32 v48, v48, v46, v47
	v_max3_f32 v48, v48, v16, v17
	v_max3_f32 v48, v48, v18, v19
	v_max3_f32 v48, v48, v20, v21
	v_max3_f32 v48, v48, v22, v23
	v_max3_f32 v48, v48, v24, v25
	v_max3_f32 v48, v48, v26, v27
	v_max3_f32 v48, v48, v28, v29
	v_max3_f32 v48, v48, v30, v31
	v_mov_b32_e32 v49, v48
	s_nop 1
	v_permlane32_swap_b32_e32 v48, v49
	v_max_f32_e32 v49, v49, v49
	v_max_f32_e32 v48, v48, v48
	v_max_f32_e32 v48, v48, v49
	v_sub_f32_e32 v36, v36, v48
	v_sub_f32_e32 v37, v37, v48
	v_exp_f32_e32 v53, v36
	v_exp_f32_e32 v54, v37
	v_lshl_add_u64 v[36:37], s[6:7], 0, v[170:171]
	v_add_co_u32_e32 v36, vcc, s33, v36
	v_sub_f32_e32 v32, v32, v48
	v_sub_f32_e32 v33, v33, v48
	v_sub_f32_e32 v34, v34, v48
	v_sub_f32_e32 v35, v35, v48
	v_sub_f32_e32 v38, v38, v48
	v_sub_f32_e32 v39, v39, v48
	v_sub_f32_e32 v40, v40, v48
	v_sub_f32_e32 v41, v41, v48
	v_sub_f32_e32 v42, v42, v48
	v_sub_f32_e32 v43, v43, v48
	v_sub_f32_e32 v44, v44, v48
	v_sub_f32_e32 v45, v45, v48
	v_sub_f32_e32 v46, v46, v48
	v_sub_f32_e32 v47, v47, v48
	v_addc_co_u32_e32 v37, vcc, 0, v37, vcc
	v_exp_f32_e32 v49, v32
	v_exp_f32_e32 v50, v33
	v_exp_f32_e32 v51, v34
	v_exp_f32_e32 v52, v35
	v_exp_f32_e32 v55, v38
	v_exp_f32_e32 v56, v39
	v_exp_f32_e32 v57, v40
	v_exp_f32_e32 v58, v41
	v_exp_f32_e32 v59, v42
	v_exp_f32_e32 v64, v43
	v_exp_f32_e32 v65, v44
	v_exp_f32_e32 v66, v45
	v_exp_f32_e32 v46, v46
	v_exp_f32_e32 v47, v47
	v_cvt_pk_bf16_f32 v144, v49, v50
	v_cvt_pk_bf16_f32 v145, v51, v52
	v_cvt_pk_bf16_f32 v146, v53, v54
	v_cvt_pk_bf16_f32 v147, v55, v56
	v_cvt_pk_bf16_f32 v140, v57, v58
	v_cvt_pk_bf16_f32 v141, v59, v64
	v_cvt_pk_bf16_f32 v142, v65, v66
	v_cvt_pk_bf16_f32 v143, v46, v47
	global_load_dwordx4 v[32:35], v170, s[6:7]
	s_nop 0
	global_load_dwordx4 v[36:39], v[36:37], off
	s_nop 0
	global_load_dwordx4 v[40:43], v60, s[8:9]
	s_add_u32 s6, s28, s47
	s_addc_u32 s7, s29, s46
	global_load_dwordx4 v[128:131], v60, s[6:7]
	s_add_u32 s6, s39, s47
	s_addc_u32 s7, s42, s46
	v_lshl_add_u64 v[44:45], s[6:7], 0, v[170:171]
	v_add_co_u32_e32 v44, vcc, s33, v44
	v_add_f32_e32 v212, 0, v48
	s_nop 0
	v_addc_co_u32_e32 v45, vcc, 0, v45, vcc
	global_load_dwordx4 v[136:139], v[44:45], off
	global_load_dwordx4 v[132:135], v170, s[6:7]
	s_waitcnt vmcnt(3)
	s_waitcnt vmcnt(5)
	ds_write_b128 v205, v[32:35] offset:16384
	s_waitcnt vmcnt(4)
	ds_write_b128 v206, v[36:39] offset:16384
	s_waitcnt vmcnt(3)
	ds_write_b128 v207, v[40:43] offset:40960
	v_add_f32_e32 v32, 0, v49
	v_add_f32_e32 v32, v50, v32
	v_add_f32_e32 v32, v51, v32
	v_add_f32_e32 v32, v52, v32
	v_add_f32_e32 v32, v53, v32
	v_add_f32_e32 v32, v54, v32
	v_add_f32_e32 v32, v55, v32
	v_add_f32_e32 v32, v56, v32
	v_add_f32_e32 v32, v57, v32
	v_add_f32_e32 v32, v58, v32
	v_add_f32_e32 v32, v59, v32
	v_add_f32_e32 v32, v64, v32
	v_add_f32_e32 v32, v65, v32
	v_add_f32_e32 v32, v66, v32
	v_add_f32_e32 v32, v46, v32
	s_addk_i32 s0, 0x4000
	v_xor_b32_e32 v96, 0x80000000, v212
	v_add_f32_e32 v164, v47, v32
	v_sub_f32_e32 v95, v31, v48
	v_sub_f32_e32 v94, v30, v48
	v_sub_f32_e32 v93, v29, v48
	v_sub_f32_e32 v92, v28, v48
	v_sub_f32_e32 v91, v27, v48
	v_sub_f32_e32 v90, v26, v48
	v_sub_f32_e32 v89, v25, v48
	v_sub_f32_e32 v88, v24, v48
	v_sub_f32_e32 v87, v23, v48
	v_sub_f32_e32 v86, v22, v48
	v_sub_f32_e32 v85, v21, v48
	v_sub_f32_e32 v84, v20, v48
	v_sub_f32_e32 v83, v19, v48
	v_sub_f32_e32 v82, v18, v48
	v_sub_f32_e32 v81, v17, v48
	v_sub_f32_e32 v80, v16, v48
	v_add_u32_e32 v202, s0, v63
	v_mov_b64_e32 v[62:63], v[14:15]
	v_mov_b64_e32 v[46:47], v[14:15]
	v_mov_b64_e32 v[30:31], v[14:15]
	s_mov_b64 s[8:9], 0
	v_mov_b64_e32 v[60:61], v[12:13]
	v_mov_b64_e32 v[58:59], v[10:11]
	v_mov_b64_e32 v[56:57], v[8:9]
	v_mov_b64_e32 v[54:55], v[6:7]
	v_mov_b64_e32 v[52:53], v[4:5]
	v_mov_b64_e32 v[50:51], v[2:3]
	v_mov_b64_e32 v[48:49], v[0:1]
	v_mov_b64_e32 v[44:45], v[12:13]
	v_mov_b64_e32 v[42:43], v[10:11]
	v_mov_b64_e32 v[40:41], v[8:9]
	v_mov_b64_e32 v[38:39], v[6:7]
	v_mov_b64_e32 v[36:37], v[4:5]
	v_mov_b64_e32 v[34:35], v[2:3]
	v_mov_b64_e32 v[32:33], v[0:1]
	v_mov_b64_e32 v[28:29], v[12:13]
	v_mov_b64_e32 v[26:27], v[10:11]
	v_mov_b64_e32 v[24:25], v[8:9]
	v_mov_b64_e32 v[22:23], v[6:7]
	v_mov_b64_e32 v[20:21], v[4:5]
	v_mov_b64_e32 v[18:19], v[2:3]
	v_mov_b64_e32 v[16:17], v[0:1]
	v_mov_b32_e32 v97, v96
	v_mov_b32_e32 v98, v96
	v_mov_b32_e32 v99, v96
	v_mov_b32_e32 v100, v96
	v_mov_b32_e32 v101, v96
	v_mov_b32_e32 v102, v96
	v_mov_b32_e32 v103, v96
	v_mov_b32_e32 v104, v96
	v_mov_b32_e32 v105, v96
	v_mov_b32_e32 v106, v96
	v_mov_b32_e32 v107, v96
	v_mov_b32_e32 v108, v96
	v_mov_b32_e32 v109, v96
	v_mov_b32_e32 v110, v96
	v_mov_b32_e32 v111, v96
	s_waitcnt lgkmcnt(0)
	s_barrier
	s_mov_b32 s100, 0x14800
	s_mov_b32 s101, 0x18010
	v_add_u32_e32 v205, s100, v205
	v_add_u32_e32 v206, s100, v206
	v_add_u32_e32 v207, s101, v207
	v_readfirstlane_b32 s0, v168
	s_nop 3
	s_lshr_b32 s0, s0, 8
	s_cmp_eq_u32 s0, 0
	s_cbranch_scc0 .Lprio_skip
	s_setprio 1
